# attention: V fragment reads issued per freed register slot during QK; static priority on waves 0-3
# speedup vs baseline: 1.0717x; 1.0168x over previous
; __device__ __forceinline__ int v_st(int k, int c) { const int kk = (k & ~0xC) | ((k & 4) << 1) | ((k & 8) >> 1); return ((kk >> 3) * 4 + (c >> 5)) * 512 + ((kk & 7) * 32 + (c & 31)) * 2; }
; __device__ __forceinline__ int v_rd_base(int lane) { return ((lane & 3) << 3) | (((lane >> 2) & 3) << 6) | (((lane >> 4) & 1) << 5) | (((lane >> 5) & 1) << 8); }
; #define SLOAD(i, k0) do { sr_[i].vs0 = *reinterpret_cast<const bf16x8*>(&Vh[(long)((k0) + sr) * LDQ + sc]); sr_[i].vs1 = *reinterpret_cast<const bf16x8*>(&Vh[(long)((k0) + 32 + sr) * LDQ + sc]); \
;     sr_[i].ks0 = *reinterpret_cast<const bf16x8*>(&Kh[(long)((k0) + kr) * LDQ + kc]); } while (0)
; #define SWAIT() asm volatile("s_waitcnt vmcnt(3)" ::: "memory")
; __device__ __forceinline__ void attn_unit(const bf16_t* __restrict__ Qb, const bf16_t* __restrict__ Kh, const bf16_t* __restrict__ Vh, int seq, char* lds,
;                                           int mode, float* scratch, float lam, float gscale, const float* __restrict__ subg, bf16_t* outp) {
;   int tid_ = threadIdx.x; asm volatile("" : "+v"(tid_));
;   const int tid = tid_, wid = tid >> 6, lane = tid & 63, r32 = lane & 31, hi = lane >> 5;
;   char* V_lds = lds; char* K_lds = lds + 3 * SHM_V;
;   float* ws = (float*)(lds + 3 * SHM_V + 3 * SHM_K) + wid * 64; float* li_l = ws; float* al_l = ws + 32;
;   float m_reg = 0.f, l_reg = 0; f32x16 o[4] = {}; bf16x8 qr[4];
;   const bf16_t* Qw = Qb + (long)(wid * QBLK + r32) * LDQ + hi * 8;
; #pragma unroll
;   for (int d0 = 0; d0 < 4; ++d0) qr[d0] = *reinterpret_cast<const bf16x8*>(Qw + d0 * 16);
;   const int sr = tid >> 4, sc = (tid & 15) * 8, vst0 = v_st(sr, sc), vst1 = v_st(32 + sr, sc);
;   const int kr = tid >> 3, kc = (tid & 7) * 8, kst = KSWZ(kr, kc * 2);
;   const int vb0 = (int)(uintptr_t)V_lds + v_rd_base(lane);
;   struct { bf16x8 vs0, vs1, ks0; } sr_[2];
;     ...
;   f32x16 pA0, pA1, pB0, pB1; float alA, alB; bf16x8 pa0, pa1, pa2, pa3; const int NT = seq / KVBLK;
;   constexpr int SE = 0, SO = 1;
;   SLOAD(SE, 0); asm volatile("s_waitcnt vmcnt(0)" ::: "memory"); SWRITE(0, SE); __syncthreads();
;   qkt(pA0, pA1, K_lds, qr, r32, hi, m_reg); partialSM(pA0, pA1, m_reg, alA, true);
;   SLOAD(SO, KVBLK); if (2 < NT) SLOAD(SE, 2 * KVBLK);
;   SWAIT(); SWRITE(1, SO); __syncthreads();
.LBB0_1329:
	v_mov_b32_e32 v56, v214
	s_or_b32 s52, s24, s76
	v_ashrrev_i32_e32 v57, 6, v56
	v_and_b32_e32 v165, 31, v56
	v_lshlrev_b32_e32 v152, 5, v57
	s_lshl_b64 s[0:1], s[52:53], 1
	v_or_b32_e32 v0, v152, v165
	s_add_u32 s58, s74, s0
	v_ashrrev_i32_e32 v1, 31, v0
	s_addc_u32 s59, s75, s1
	v_bfe_u32 v164, v56, 5, 1
	v_lshlrev_b64 v[0:1], 10, v[0:1]
	v_lshl_add_u64 v[0:1], s[58:59], 0, v[0:1]
	v_lshlrev_b32_e32 v178, 4, v164
	v_lshl_add_u64 v[0:1], v[0:1], 0, v[178:179]
	global_load_dwordx4 v[124:127], v[0:1], off
	global_load_dwordx4 v[120:123], v[0:1], off offset:32
	global_load_dwordx4 v[116:119], v[0:1], off offset:64
	global_load_dwordx4 v[112:115], v[0:1], off offset:96
	v_ashrrev_i32_e32 v0, 4, v56
	v_and_b32_e32 v1, 0xfffff0, v0
	v_lshlrev_b32_e32 v3, 1, v0
	v_lshlrev_b32_e32 v12, 3, v56
	v_and_or_b32 v1, v3, 8, v1
	v_lshrrev_b32_e32 v3, 1, v0
	v_lshrrev_b32_e32 v1, 1, v1
	v_bfe_u32 v5, v12, 5, 2
	v_and_b32_e32 v4, 3, v0
	v_or_b32_e32 v1, v1, v5
	v_and_or_b32 v3, v3, 4, v4
	v_lshlrev_b32_e32 v6, 4, v56
	v_lshlrev_b32_e32 v1, 9, v1
	v_lshlrev_b32_e32 v3, 6, v3
	v_and_b32_e32 v7, 48, v6
	v_add_u32_e32 v4, 32, v0
	v_or3_b32 v168, v1, v3, v7
	v_and_b32_e32 v1, 0xfffff0, v4
	v_lshlrev_b32_e32 v8, 1, v4
	v_and_or_b32 v1, v8, 8, v1
	v_lshrrev_b32_e32 v1, 1, v1
	v_or_b32_e32 v1, v1, v5
	v_lshlrev_b32_e32 v1, 9, v1
	v_ashrrev_i32_e32 v8, 3, v56
	v_or3_b32 v169, v1, v3, v7
	v_lshrrev_b32_e32 v232, 7, v56
	v_lshlrev_b32_e32 v232, 11, v232
	v_bfe_u32 v233, v56, 2, 2
	v_lshl_or_b32 v232, v233, 9, v232
	v_bfe_u32 v233, v56, 4, 3
	v_lshl_or_b32 v232, v233, 6, v232
	v_and_b32_e32 v233, 3, v56
	v_lshl_or_b32 v168, v233, 4, v232
	v_add_u32_e32 v169, 0x2000, v168
	v_lshlrev_b32_e32 v1, 7, v8
	v_and_b32_e32 v10, 0x70, v6
	v_and_b32_e32 v3, 0x70, v56
	v_bitop3_b32 v170, v10, v1, v3 bitop3:0xde
	v_ashrrev_i32_e32 v1, 31, v0
	v_ashrrev_i32_e32 v5, 31, v4
	s_add_u32 s20, s77, s0
	v_and_b32_e32 v2, 0x78, v12
	v_lshlrev_b64 v[48:49], 10, v[0:1]
	v_lshlrev_b64 v[4:5], 10, v[4:5]
	v_ashrrev_i32_e32 v9, 31, v8
	s_addc_u32 s21, s78, s1
	v_lshl_add_u64 v[0:1], s[18:19], 0, v[48:49]
	v_lshlrev_b32_e32 v6, 1, v2
	v_mov_b32_e32 v7, v179
	v_lshl_add_u64 v[4:5], s[18:19], 0, v[4:5]
	v_lshlrev_b64 v[50:51], 10, v[8:9]
	v_lshl_add_u64 v[52:53], v[0:1], 0, v[6:7]
	v_lshl_add_u64 v[4:5], v[4:5], 0, v[6:7]
	v_lshl_add_u64 v[8:9], s[20:21], 0, v[50:51]
	v_mov_b32_e32 v11, v179
	global_load_dwordx4 v[0:3], v[52:53], off
	v_lshl_add_u64 v[54:55], v[8:9], 0, v[10:11]
	global_load_dwordx4 v[4:7], v[4:5], off
	v_lshlrev_b32_e32 v64, 7, v165
	global_load_dwordx4 v[8:11], v[54:55], off
	v_and_b32_e32 v65, 0x70, v12
	v_add_u32_e32 v58, 0, v168
	v_add_u32_e32 v59, 0, v169
	v_bitop3_b32 v173, v178, v64, v65 bitop3:0xde
	s_waitcnt vmcnt(0)
	v_add_u32_e32 v171, 0, v170
	v_mov_b64_e32 v[32:33], s[36:37]
	v_mov_b64_e32 v[34:35], s[38:39]
	v_mov_b64_e32 v[36:37], s[40:41]
	v_mov_b64_e32 v[38:39], s[42:43]
	v_mov_b64_e32 v[40:41], s[44:45]
	v_mov_b64_e32 v[42:43], s[46:47]
	v_mov_b64_e32 v[44:45], s[48:49]
	v_mov_b64_e32 v[46:47], s[50:51]
	s_mov_b32 s0, 0x18000
	s_waitcnt vmcnt(2)
	ds_write_b128 v58, v[0:3]
	s_waitcnt vmcnt(1)
	ds_write_b128 v59, v[4:7]
	v_add_u32_e32 v4, 0, v173
	s_waitcnt vmcnt(0)
	ds_write_b128 v171, v[8:11] offset:49152
	s_waitcnt lgkmcnt(0)
	s_barrier
	ds_read_b128 v[0:3], v4 offset:49152
	ds_read_b128 v[60:63], v4 offset:53248
	s_waitcnt lgkmcnt(1)
	v_mfma_f32_32x32x16_bf16 v[16:31], v[0:3], v[124:127], v[32:47]
	s_waitcnt lgkmcnt(0)
	v_mfma_f32_32x32x16_bf16 v[0:15], v[60:63], v[124:127], v[32:47]
	s_nop 6
	v_or_b32_e32 v32, 32, v178
	v_bitop3_b32 v175, v32, v64, v65 bitop3:0xde
	v_add_u32_e32 v36, 0, v175
	ds_read_b128 v[32:35], v36 offset:49152
	ds_read_b128 v[36:39], v36 offset:53248
	s_waitcnt lgkmcnt(1)
	v_mfma_f32_32x32x16_bf16 v[16:31], v[32:35], v[120:123], v[16:31]
	v_or_b32_e32 v32, 64, v178
	v_bitop3_b32 v174, v32, v64, v65 bitop3:0xde
	s_waitcnt lgkmcnt(0)
	v_mfma_f32_32x32x16_bf16 v[0:15], v[36:39], v[120:123], v[0:15]
	v_add_u32_e32 v36, 0, v174
	ds_read_b128 v[32:35], v36 offset:49152
	ds_read_b128 v[36:39], v36 offset:53248
	s_waitcnt lgkmcnt(1)
	v_mfma_f32_32x32x16_bf16 v[16:31], v[32:35], v[116:119], v[16:31]
	v_or_b32_e32 v32, 0x60, v178
	v_bitop3_b32 v176, v32, v64, v65 bitop3:0xde
	s_waitcnt lgkmcnt(0)
	v_mfma_f32_32x32x16_bf16 v[0:15], v[36:39], v[116:119], v[0:15]
	v_add_u32_e32 v36, 0, v176
	ds_read_b128 v[32:35], v36 offset:49152
	ds_read_b128 v[36:39], v36 offset:53248
	s_waitcnt lgkmcnt(1)
	v_mfma_f32_32x32x16_bf16 v[16:31], v[32:35], v[112:115], v[16:31]
	s_waitcnt lgkmcnt(0)
	v_mfma_f32_32x32x16_bf16 v[0:15], v[36:39], v[112:115], v[0:15]
	s_nop 9
	v_max_f32_e32 v32, v17, v17
	v_max_f32_e32 v33, v16, v16
	v_max_f32_e32 v32, v33, v32
	v_max3_f32 v32, v32, v18, v19
	v_max3_f32 v32, v32, v20, v21
	v_max3_f32 v32, v32, v22, v23
	v_max3_f32 v32, v32, v24, v25
	v_max3_f32 v32, v32, v26, v27
	v_max3_f32 v32, v32, v28, v29
	v_max3_f32 v32, v32, v30, v31
	v_max3_f32 v32, v32, v0, v1
	v_max3_f32 v32, v32, v2, v3
	v_max3_f32 v32, v32, v4, v5
	v_max3_f32 v32, v32, v6, v7
	v_max3_f32 v32, v32, v8, v9
	v_max3_f32 v32, v32, v10, v11
	v_max3_f32 v32, v32, v12, v13
	v_max3_f32 v36, v32, v14, v15
	v_add_co_u32_e32 v32, vcc, s63, v52
	v_mov_b32_e32 v37, v36
	s_nop 0
	v_addc_co_u32_e32 v33, vcc, 0, v53, vcc
	v_add_co_u32_e32 v38, vcc, s0, v52
	s_mov_b32 s0, 0x20000
	s_nop 0
	v_addc_co_u32_e32 v39, vcc, 0, v53, vcc
	v_add_co_u32_e32 v42, vcc, s63, v54
	global_load_dwordx4 v[32:35], v[32:33], off
	s_nop 0
	v_addc_co_u32_e32 v43, vcc, 0, v55, vcc
	v_add_co_u32_e32 v46, vcc, s0, v52
	global_load_dwordx4 v[42:45], v[42:43], off
	s_nop 0
	v_addc_co_u32_e32 v47, vcc, 0, v53, vcc
	global_load_dwordx4 v[128:131], v[46:47], off
	v_add_co_u32_e32 v46, vcc, 0x28000, v52
	global_load_dwordx4 v[38:41], v[38:39], off
	s_nop 0
	v_addc_co_u32_e32 v47, vcc, 0, v53, vcc
	global_load_dwordx4 v[132:135], v[46:47], off
	v_add_co_u32_e32 v46, vcc, 0x20000, v54
	v_permlane32_swap_b32_e32 v36, v37
	s_nop 0
	v_addc_co_u32_e32 v47, vcc, 0, v55, vcc
	global_load_dwordx4 v[136:139], v[46:47], off
	s_waitcnt vmcnt(3)
	v_cmp_lt_i32_e32 vcc, 3, v57
	s_waitcnt vmcnt(5)
	ds_write_b128 v58, v[32:35] offset:16384
	s_waitcnt vmcnt(2)
	ds_write_b128 v59, v[38:41] offset:16384
	ds_write_b128 v171, v[42:45] offset:57344
	s_waitcnt lgkmcnt(0)
	s_barrier
; #define SLOAD(i, k0) do { sr_[i].vs0 = *reinterpret_cast<const bf16x8*>(&Vh[(long)((k0) + sr) * LDQ + sc]); sr_[i].vs1 = *reinterpret_cast<const bf16x8*>(&Vh[(long)((k0) + 32 + sr) * LDQ + sc]); \
;     sr_[i].ks0 = *reinterpret_cast<const bf16x8*>(&Kh[(long)((k0) + kr) * LDQ + kc]); } while (0)
; #define SWRITE(b, i) do { *(bf16x8*)(V_lds + (b) * SHM_V + vst0) = sr_[i].vs0; *(bf16x8*)(V_lds + (b) * SHM_V + vst1) = sr_[i].vs1; \
;     *(bf16x8*)(K_lds + (b) * SHM_K + kst) = sr_[i].ks0; } while (0)
; #define SWAIT() asm volatile("s_waitcnt vmcnt(3)" ::: "memory")
; __device__ __forceinline__ void attn_unit(const bf16_t* __restrict__ Qb, const bf16_t* __restrict__ Kh, const bf16_t* __restrict__ Vh, int seq, char* lds,
;                                           int mode, float* scratch, float lam, float gscale, const float* __restrict__ subg, bf16_t* outp) {
;     ...
;   f32x16 pA0, pA1, pB0, pB1; float alA, alB; bf16x8 pa0, pa1, pa2, pa3; const int NT = seq / KVBLK;
;   constexpr int SE = 0, SO = 1;
;   SLOAD(SE, 0); asm volatile("s_waitcnt vmcnt(0)" ::: "memory"); SWRITE(0, SE); __syncthreads();
;   qkt(pA0, pA1, K_lds, qr, r32, hi, m_reg); partialSM(pA0, pA1, m_reg, alA, true);
;   SLOAD(SO, KVBLK); if (2 < NT) SLOAD(SE, 2 * KVBLK);
;   SWAIT(); SWRITE(1, SO); __syncthreads();
;   int bp = 0, bc = 1, bn = 2;
;     ...
;   if (wid >= 4) __builtin_amdgcn_s_setprio(1);
	s_and_saveexec_b64 s[20:21], vcc
	s_setprio 1
	s_or_b64 exec, exec, s[20:21]
	v_max_f32_e32 v33, v37, v37
	v_max_f32_e32 v34, v36, v36
	v_max_f32_e32 v33, v34, v33
	s_xor_b64 s[72:73], s[4:5], -1
	s_add_i32 s1, 0, 0x14000
	v_sub_f32_e32 v64, v0, v33
	v_and_b32_e32 v0, 15, v56
	v_and_b32_e32 v32, 63, v56
	v_sub_f32_e32 v16, v16, v33
	v_sub_f32_e32 v17, v17, v33
	s_cmp_lg_u32 0, -1
	v_sub_f32_e32 v65, v1, v33
	v_lshlrev_b32_e32 v0, 4, v0
	v_mov_b32_e32 v1, v179
	v_sub_f32_e32 v18, v18, v33
	v_exp_f32_e32 v160, v16
	v_exp_f32_e32 v192, v17
	v_and_b32_e32 v16, 0x3fffffc0, v56
	v_lshlrev_b32_e32 v17, 4, v32
	s_cselect_b32 s4, 0, 0
	v_lshl_add_u64 v[0:1], v[48:49], 0, v[0:1]
	s_add_i32 s52, s71, s24
	v_sub_f32_e32 v19, v19, v33
	v_sub_f32_e32 v20, v20, v33
	v_sub_f32_e32 v21, v21, v33
	v_sub_f32_e32 v22, v22, v33
	v_sub_f32_e32 v23, v23, v33
	v_sub_f32_e32 v24, v24, v33
	v_sub_f32_e32 v25, v25, v33
	v_sub_f32_e32 v26, v26, v33
	v_sub_f32_e32 v27, v27, v33
	v_sub_f32_e32 v28, v28, v33
	v_sub_f32_e32 v29, v29, v33
	v_sub_f32_e32 v30, v30, v33
	v_sub_f32_e32 v31, v31, v33
	v_exp_f32_e32 v151, v18
	v_lshl_add_u32 v166, v16, 2, s1
	v_lshlrev_b32_e32 v16, 3, v32
	v_and_b32_e32 v17, 0xc0, v17
	v_lshlrev_b32_e32 v18, 1, v32
	v_lshl_add_u64 v[154:155], s[28:29], 0, v[0:1]
	v_and_b32_e32 v0, 7, v56
	s_lshl_b64 s[20:21], s[52:53], 1
	v_exp_f32_e32 v161, v19
	v_exp_f32_e32 v149, v20
	v_exp_f32_e32 v159, v21
	v_exp_f32_e32 v148, v22
	v_exp_f32_e32 v150, v23
	v_exp_f32_e32 v145, v24
	v_exp_f32_e32 v147, v25
	v_exp_f32_e32 v143, v26
	v_exp_f32_e32 v146, v27
	v_exp_f32_e32 v141, v28
	v_exp_f32_e32 v144, v29
	v_exp_f32_e32 v140, v30
	v_exp_f32_e32 v142, v31
	v_and_or_b32 v17, v16, 24, v17
	v_and_b32_e32 v18, 32, v18
	v_and_b32_e32 v16, 0x100, v16
	v_lshlrev_b32_e32 v0, 4, v0
	v_mov_b32_e32 v1, v179
	s_add_u32 s20, s10, s20
	v_or3_b32 v16, v17, v18, v16
	v_sub_f32_e32 v79, v15, v33
	v_sub_f32_e32 v78, v14, v33
	v_lshl_add_u64 v[0:1], v[50:51], 0, v[0:1]
	s_addc_u32 s21, s11, s21
	v_mov_b32_e32 v14, v179
	v_mov_b32_e32 v15, v179
	v_add_u32_e32 v177, s4, v16
	v_add_f32_e32 v181, 0, v33
	v_sub_f32_e32 v77, v13, v33
	v_sub_f32_e32 v76, v12, v33
	v_sub_f32_e32 v75, v11, v33
	v_sub_f32_e32 v74, v10, v33
	v_sub_f32_e32 v73, v9, v33
	v_sub_f32_e32 v72, v8, v33
	v_sub_f32_e32 v71, v7, v33
	v_sub_f32_e32 v70, v6, v33
	v_sub_f32_e32 v69, v5, v33
	v_sub_f32_e32 v68, v4, v33
	v_sub_f32_e32 v67, v3, v33
	v_sub_f32_e32 v66, v2, v33
	v_cmp_gt_u32_e64 s[4:5], 32, v32
	v_lshl_add_u64 v[156:157], s[20:21], 0, v[0:1]
	v_mov_b32_e32 v0, v179
	v_mov_b32_e32 v1, v179
	v_mov_b32_e32 v2, v179
	v_mov_b32_e32 v3, v179
	v_mov_b32_e32 v4, v179
	v_mov_b32_e32 v5, v179
	v_mov_b32_e32 v6, v179
	v_mov_b32_e32 v7, v179
	v_mov_b32_e32 v8, v179
	v_mov_b32_e32 v9, v179
	v_mov_b32_e32 v10, v179
	v_mov_b32_e32 v11, v179
	v_mov_b32_e32 v12, v179
	v_mov_b32_e32 v13, v179
	v_mov_b64_e32 v[62:63], v[14:15]
	v_mov_b64_e32 v[46:47], v[14:15]
	v_mov_b64_e32 v[30:31], v[14:15]
	s_mov_b32 s0, 2
	s_mov_b32 s1, 1
	s_mov_b32 s2, 0
	v_lshl_add_u32 v153, v165, 2, v166
	v_mov_b32_e32 v167, 0
	v_mov_b32_e32 v186, 1.0
	v_mov_b64_e32 v[60:61], v[12:13]
	v_mov_b64_e32 v[58:59], v[10:11]
	v_mov_b64_e32 v[56:57], v[8:9]
	v_mov_b64_e32 v[54:55], v[6:7]
	v_mov_b64_e32 v[52:53], v[4:5]
	v_mov_b64_e32 v[50:51], v[2:3]
	v_mov_b64_e32 v[48:49], v[0:1]
	v_mov_b64_e32 v[44:45], v[12:13]
	v_mov_b64_e32 v[42:43], v[10:11]
	v_mov_b64_e32 v[40:41], v[8:9]
	v_mov_b64_e32 v[38:39], v[6:7]
	v_mov_b64_e32 v[36:37], v[4:5]
	v_mov_b64_e32 v[34:35], v[2:3]
	v_mov_b64_e32 v[32:33], v[0:1]
	v_mov_b64_e32 v[28:29], v[12:13]
	v_mov_b64_e32 v[26:27], v[10:11]
	v_mov_b64_e32 v[24:25], v[8:9]
	v_mov_b64_e32 v[22:23], v[6:7]
	v_mov_b64_e32 v[20:21], v[4:5]
	v_mov_b64_e32 v[18:19], v[2:3]
	v_mov_b64_e32 v[16:17], v[0:1]
	s_mov_b32 s52, 1
	v_exp_f32_e32 v80, v64
	v_exp_f32_e32 v81, v65
	v_exp_f32_e32 v82, v66
	v_exp_f32_e32 v83, v67
	v_exp_f32_e32 v84, v68
	v_exp_f32_e32 v85, v69
	v_exp_f32_e32 v86, v70
	v_exp_f32_e32 v87, v71
	v_exp_f32_e32 v88, v72
	v_exp_f32_e32 v89, v73
	v_exp_f32_e32 v90, v74
	v_exp_f32_e32 v91, v75
	v_exp_f32_e32 v92, v76
	v_exp_f32_e32 v93, v77
	v_exp_f32_e32 v94, v78
	v_exp_f32_e32 v95, v79
	v_mov_b32_e32 v64, v160
	v_mov_b32_e32 v65, v192
	v_mov_b32_e32 v66, v151
	v_mov_b32_e32 v67, v161
	v_mov_b32_e32 v68, v149
	v_mov_b32_e32 v69, v159
	v_mov_b32_e32 v70, v148
	v_mov_b32_e32 v71, v150
	v_mov_b32_e32 v72, v145
	v_mov_b32_e32 v73, v147
	v_mov_b32_e32 v74, v143
	v_mov_b32_e32 v75, v146
	v_mov_b32_e32 v76, v141
	v_mov_b32_e32 v77, v144
	v_mov_b32_e32 v78, v140
	v_mov_b32_e32 v79, v142
	v_mov_b32_e32 v235, v186
	v_readfirstlane_b32 s24, v156
	v_readfirstlane_b32 s25, v157
	v_readfirstlane_b32 s79, v214
	v_readfirstlane_b32 s58, v154
	s_nop 3
	s_lshr_b32 s79, s79, 6
	s_lshl_b32 s20, s79, 13
	s_sub_u32 s24, s24, s20
	s_subb_u32 s25, s25, 0
	s_lshl_b32 s20, s79, 12
	s_sub_i32 s58, s58, s20
	s_sub_i32 s58, s58, s24
	s_add_i32 s58, s58, 0x2000000
	s_lshl_b32 s79, s79, 10
	s_add_u32 s24, s24, s16
	s_addc_u32 s25, s25, s17
	s_add_u32 s24, s24, 0x15c20000
	s_addc_u32 s25, s25, 0
	v_lshrrev_b32_e32 v217, 6, v214
	v_lshlrev_b32_e32 v217, 13, v217
	v_bfe_u32 v218, v214, 2, 3
	v_lshl_add_u32 v217, v218, 10, v217
	v_bfe_u32 v218, v214, 5, 1
	v_lshl_add_u32 v217, v218, 6, v217
	v_and_b32_e32 v218, 3, v214
	v_lshl_add_u32 v217, v218, 4, v217
	v_add_u32_e32 v233, s58, v217
	v_add_u32_e32 v234, 0x80, v233
	v_lshrrev_b32_e32 v217, 3, v214
	v_lshlrev_b32_e32 v217, 10, v217
	v_bfe_u32 v218, v214, 4, 3
	v_and_b32_e32 v232, 7, v214
	v_xor_b32_e32 v232, v232, v218
	v_lshl_add_u32 v232, v232, 4, v217
	v_add_u32_e32 v217, 0x10000, v232
	v_add_u32_e32 v232, 0x20000, v232
	s_waitcnt vmcnt(0)
	v_add_u32_e32 v218, 0x4000, v170
	ds_write_b128 v218, v[136:139] offset:49152
	s_add_i32 m0, s79, 0x12000
	s_nop 0
	global_load_lds_dwordx4 v217, s[24:25]
	v_readfirstlane_b32 s58, v214
	s_setprio 0
	s_lshr_b32 s58, s58, 8
	s_cmp_lg_u32 s58, 0
	s_cbranch_scc1 .Lat_noprio
	s_setprio 1

; #define SBAR() __builtin_amdgcn_sched_barrier(0)
; __device__ __forceinline__ void qkt(f32x16& p0, f32x16& p1, const char* Ks, const bf16x8* qr, int r32, int hi, float m_ref) {
; #pragma unroll
;   for (int r = 0; r < 16; ++r) { p0[r] = -m_ref; p1[r] = -m_ref; }
; #pragma unroll
;   for (int d0 = 0; d0 < 4; ++d0) { const int cb = (d0 * 16 + hi * 8) * 2;
;     bf16x8 b0 = *reinterpret_cast<const bf16x8*>(Ks + KSWZ(r32, cb));
;     bf16x8 b1 = *reinterpret_cast<const bf16x8*>(Ks + KSWZ(32 + r32, cb));
;     p0 = __builtin_amdgcn_mfma_f32_32x32x16_bf16(b0, qr[d0], p0, 0, 0, 0);
;     p1 = __builtin_amdgcn_mfma_f32_32x32x16_bf16(b1, qr[d0], p1, 0, 0, 0); }
; }
; __device__ __forceinline__ int v_st(int k, int c) { const int kk = (k & ~0xC) | ((k & 4) << 1) | ((k & 8) >> 1); return ((kk >> 3) * 4 + (c >> 5)) * 512 + ((kk & 7) * 32 + (c & 31)) * 2; }
; __device__ __forceinline__ int v_rd_base(int lane) { return ((lane & 3) << 3) | (((lane >> 2) & 3) << 6) | (((lane >> 4) & 1) << 5) | (((lane >> 5) & 1) << 8); }
; template <int OFF> __device__ __forceinline__ s16x4 tr_read(int vb) {
;   s16x4 r; asm volatile("ds_read_b64_tr_b16 %0, %1 offset:%2" : "=&v"(r) : "v"(vb), "i"(OFF) : "memory"); return r;
; }
; template <int D0> __device__ __forceinline__ void pv_one(f32x16& od, int vb, bf16x8 pa0, bf16x8 pa1, bf16x8 pa2, bf16x8 pa3) {
;   const s16x4 l0 = tr_read<v_rd_off(D0, 0, 0)>(vb), h0 = tr_read<v_rd_off(D0, 0, 1)>(vb), l1 = tr_read<v_rd_off(D0, 1, 0)>(vb), h1 = tr_read<v_rd_off(D0, 1, 1)>(vb);
;   const s16x4 l2 = tr_read<v_rd_off(D0, 2, 0)>(vb), h2 = tr_read<v_rd_off(D0, 2, 1)>(vb), l3 = tr_read<v_rd_off(D0, 3, 0)>(vb), h3 = tr_read<v_rd_off(D0, 3, 1)>(vb);
;   asm volatile("s_waitcnt lgkmcnt(0)" ::: "memory"); SBAR();
;     ...
;   od = __builtin_amdgcn_mfma_f32_32x32x16_bf16(pa0, PK(l0, h0), od, 0, 0, 0);
; __device__ __forceinline__ void attn_unit(const bf16_t* __restrict__ Qb, const bf16_t* __restrict__ Kh, const bf16_t* __restrict__ Vh, int seq, char* lds,
;                                           int mode, float* scratch, float lam, float gscale, const float* __restrict__ subg, bf16_t* outp) {
;     ...
;     SBAR(); qkt(pB0, pB1, K_lds + bc * SHM_K, qr, r32, hi, m_reg);
;     finishSM(pA0, pA1, alA, l_reg, pa0, pa1, pa2, pa3); SBAR();
;     SLOAD(SO, (j + 2) * KVBLK); SBAR();
;     pv_d0(o, vb0 + bp * SHM_V, pa0, pa1, pa2, pa3); partialSM(pB0, pB1, m_reg, alB, false);
.Lat_loop:
	s_mov_b32 s21, 0
	s_lshl_b32 s59, s2, 14
	v_add_u32_e32 v172, s59, v177
	s_lshl_b32 s20, s0, 14
	s_add_i32 s20, s20, s79
	s_add_i32 m0, s20, s79
	s_nop 0
	global_load_lds_dwordx4 v233, s[24:25]
	s_add_i32 m0, m0, 0x400
	s_nop 0
	global_load_lds_dwordx4 v234, s[24:25]
	s_add_i32 s20, s52, 3
	s_and_b32 s20, s20, 3
	s_lshl_b32 s20, s20, 13
	s_add_i32 s20, s20, s79
	s_add_i32 m0, s20, 0xc000
	s_nop 0
	global_load_lds_dwordx4 v232, s[24:25]
	s_add_u32 s24, s24, 0x10000
	s_addc_u32 s25, s25, 0
	v_add_f32_e32 v159, v64, v65
	v_cvt_pk_bf16_f32 v64, v64, v65
	v_add_f32_e32 v160, v66, v67
	v_cvt_pk_bf16_f32 v65, v66, v67
	v_add_f32_e32 v159, v68, v159
	s_waitcnt lgkmcnt(7)
	v_mfma_f32_32x32x16_bf16 v[96:111], v[182:185], v[124:127], v[128:143]
	ds_read_b64_tr_b16 v[182:183], v172 offset:0x0
	ds_read_b64_tr_b16 v[184:185], v172 offset:0x800
	v_add_f32_e32 v160, v69, v160
	v_cvt_pk_bf16_f32 v66, v68, v69
	v_add_f32_e32 v159, v70, v159
	v_add_f32_e32 v160, v71, v160
	v_cvt_pk_bf16_f32 v67, v70, v71
	v_add_f32_e32 v159, v72, v159
	s_waitcnt lgkmcnt(8)
	v_mfma_f32_32x32x16_bf16 v[236:251], v[186:189], v[124:127], v[128:143]
	ds_read_b64_tr_b16 v[186:187], v172 offset:0x1000
	ds_read_b64_tr_b16 v[188:189], v172 offset:0x1800
	v_add_f32_e32 v160, v73, v160
	v_cvt_pk_bf16_f32 v68, v72, v73
	v_add_f32_e32 v159, v74, v159
	v_add_f32_e32 v160, v75, v160
	v_cvt_pk_bf16_f32 v69, v74, v75
	s_waitcnt lgkmcnt(9)
	v_mfma_f32_32x32x16_bf16 v[96:111], v[190:193], v[120:123], v[96:111]
	ds_read_b64_tr_b16 v[190:191], v172 offset:0x2000
	ds_read_b64_tr_b16 v[192:193], v172 offset:0x2800
	v_add_f32_e32 v159, v76, v159
	v_add_f32_e32 v160, v77, v160
	v_cvt_pk_bf16_f32 v70, v76, v77
	v_add_f32_e32 v159, v78, v159
	v_add_f32_e32 v160, v79, v160
	v_cvt_pk_bf16_f32 v71, v78, v79
	s_waitcnt lgkmcnt(10)
	v_mfma_f32_32x32x16_bf16 v[236:251], v[194:197], v[120:123], v[236:251]
	ds_read_b64_tr_b16 v[194:195], v172 offset:0x3000
	ds_read_b64_tr_b16 v[196:197], v172 offset:0x3800
	v_add_f32_e32 v159, v80, v159
	v_add_f32_e32 v160, v81, v160
	v_cvt_pk_bf16_f32 v72, v80, v81
	v_add_f32_e32 v159, v82, v159
	v_add_f32_e32 v160, v83, v160
	v_cvt_pk_bf16_f32 v73, v82, v83
	s_waitcnt lgkmcnt(11)
	v_mfma_f32_32x32x16_bf16 v[96:111], v[198:201], v[116:119], v[96:111]
	ds_read_b64_tr_b16 v[198:199], v172 offset:0x200
	ds_read_b64_tr_b16 v[200:201], v172 offset:0xa00
	v_add_f32_e32 v159, v84, v159
	v_add_f32_e32 v160, v85, v160
	v_cvt_pk_bf16_f32 v74, v84, v85
	v_add_f32_e32 v159, v86, v159
	v_add_f32_e32 v160, v87, v160
	v_cvt_pk_bf16_f32 v75, v86, v87
	s_waitcnt lgkmcnt(12)
	v_mfma_f32_32x32x16_bf16 v[236:251], v[202:205], v[116:119], v[236:251]
	ds_read_b64_tr_b16 v[202:203], v172 offset:0x1200
	ds_read_b64_tr_b16 v[204:205], v172 offset:0x1a00
	v_add_f32_e32 v159, v88, v159
	v_add_f32_e32 v160, v89, v160
	v_cvt_pk_bf16_f32 v76, v88, v89
	v_add_f32_e32 v159, v90, v159
	v_add_f32_e32 v160, v91, v160
	v_cvt_pk_bf16_f32 v77, v90, v91
	v_add_f32_e32 v159, v92, v159
	s_waitcnt lgkmcnt(13)
	v_mfma_f32_32x32x16_bf16 v[96:111], v[206:209], v[112:115], v[96:111]
	ds_read_b64_tr_b16 v[206:207], v172 offset:0x2200
	ds_read_b64_tr_b16 v[208:209], v172 offset:0x2a00
	v_add_f32_e32 v160, v93, v160
	v_cvt_pk_bf16_f32 v78, v92, v93
	v_add_f32_e32 v159, v94, v159
	v_add_f32_e32 v160, v95, v160
	v_cvt_pk_bf16_f32 v79, v94, v95
	v_add_f32_e32 v159, v159, v160
	v_fma_f32 v167, v167, v235, v159
	s_waitcnt lgkmcnt(14)
	v_mfma_f32_32x32x16_bf16 v[236:251], v[210:213], v[112:115], v[236:251]
	s_waitcnt lgkmcnt(12)
	v_mfma_f32_32x32x16_bf16 v[0:15], v[64:67], v[182:185], v[0:15]
	ds_read_b64_tr_b16 v[210:211], v172 offset:0x3200
	ds_read_b64_tr_b16 v[212:213], v172 offset:0x3a00
	v_max3_f32 v161, v96, v97, v98
	v_max3_f32 v161, v161, v99, v100
	v_max3_f32 v161, v161, v101, v102
	v_max3_f32 v161, v161, v103, v104
	s_waitcnt lgkmcnt(12)
	v_mfma_f32_32x32x16_bf16 v[0:15], v[68:71], v[186:189], v[0:15]
	ds_read_b64_tr_b16 v[182:183], v172 offset:0x400
	ds_read_b64_tr_b16 v[184:185], v172 offset:0xc00
	v_max3_f32 v161, v161, v105, v106
	v_max3_f32 v161, v161, v107, v108
	v_max3_f32 v161, v161, v109, v110
	v_max_f32_e32 v161, v161, v111
	s_waitcnt lgkmcnt(12)
	v_mfma_f32_32x32x16_bf16 v[0:15], v[72:75], v[190:193], v[0:15]
	ds_read_b64_tr_b16 v[186:187], v172 offset:0x1400
	ds_read_b64_tr_b16 v[188:189], v172 offset:0x1c00
	v_max3_f32 v216, v236, v237, v238
	v_max3_f32 v216, v216, v239, v240
	v_max3_f32 v216, v216, v241, v242
	v_max3_f32 v216, v216, v243, v244
	s_waitcnt lgkmcnt(12)
	v_mfma_f32_32x32x16_bf16 v[0:15], v[76:79], v[194:197], v[0:15]
	ds_read_b64_tr_b16 v[190:191], v172 offset:0x2400
	ds_read_b64_tr_b16 v[192:193], v172 offset:0x2c00
	v_max3_f32 v216, v216, v245, v246
	v_max3_f32 v216, v216, v247, v248
	v_max3_f32 v216, v216, v249, v250
	v_max_f32_e32 v216, v216, v251
	v_max_f32_e32 v161, v161, v216
	v_cmp_ge_f32_e32 vcc, s66, v161
	s_cmp_eq_u64 vcc, exec
	s_cbranch_scc0 .Lat_rare0
	v_mov_b32_e32 v158, 1.0

; __device__ __forceinline__ void qkt(f32x16& p0, f32x16& p1, const char* Ks, const bf16x8* qr, int r32, int hi, float m_ref) {
; #pragma unroll
;   for (int r = 0; r < 16; ++r) { p0[r] = -m_ref; p1[r] = -m_ref; }
; #pragma unroll
;   for (int d0 = 0; d0 < 4; ++d0) { const int cb = (d0 * 16 + hi * 8) * 2;
;     bf16x8 b0 = *reinterpret_cast<const bf16x8*>(Ks + KSWZ(r32, cb));
;     bf16x8 b1 = *reinterpret_cast<const bf16x8*>(Ks + KSWZ(32 + r32, cb));
;     p0 = __builtin_amdgcn_mfma_f32_32x32x16_bf16(b0, qr[d0], p0, 0, 0, 0);
;     p1 = __builtin_amdgcn_mfma_f32_32x32x16_bf16(b1, qr[d0], p1, 0, 0, 0); }
; }
; __device__ __forceinline__ int v_st(int k, int c) { const int kk = (k & ~0xC) | ((k & 4) << 1) | ((k & 8) >> 1); return ((kk >> 3) * 4 + (c >> 5)) * 512 + ((kk & 7) * 32 + (c & 31)) * 2; }
; __device__ __forceinline__ int v_rd_base(int lane) { return ((lane & 3) << 3) | (((lane >> 2) & 3) << 6) | (((lane >> 4) & 1) << 5) | (((lane >> 5) & 1) << 8); }
; template <int OFF> __device__ __forceinline__ s16x4 tr_read(int vb) {
;   s16x4 r; asm volatile("ds_read_b64_tr_b16 %0, %1 offset:%2" : "=&v"(r) : "v"(vb), "i"(OFF) : "memory"); return r;
; }
; template <int D0> __device__ __forceinline__ void pv_one(f32x16& od, int vb, bf16x8 pa0, bf16x8 pa1, bf16x8 pa2, bf16x8 pa3) {
;   const s16x4 l0 = tr_read<v_rd_off(D0, 0, 0)>(vb), h0 = tr_read<v_rd_off(D0, 0, 1)>(vb), l1 = tr_read<v_rd_off(D0, 1, 0)>(vb), h1 = tr_read<v_rd_off(D0, 1, 1)>(vb);
;   const s16x4 l2 = tr_read<v_rd_off(D0, 2, 0)>(vb), h2 = tr_read<v_rd_off(D0, 2, 1)>(vb), l3 = tr_read<v_rd_off(D0, 3, 0)>(vb), h3 = tr_read<v_rd_off(D0, 3, 1)>(vb);
;   asm volatile("s_waitcnt lgkmcnt(0)" ::: "memory"); SBAR();
;     ...
;   od = __builtin_amdgcn_mfma_f32_32x32x16_bf16(pa0, PK(l0, h0), od, 0, 0, 0);
; __device__ __forceinline__ void attn_unit(const bf16_t* __restrict__ Qb, const bf16_t* __restrict__ Kh, const bf16_t* __restrict__ Vh, int seq, char* lds,
;                                           int mode, float* scratch, float lam, float gscale, const float* __restrict__ subg, bf16_t* outp) {
;     ...
;     SBAR(); qkt(pA0, pA1, K_lds + bc * SHM_K, qr, r32, hi, m_reg);
;     finishSM(pB0, pB1, alB, l_reg, pa0, pa1, pa2, pa3); SBAR();
;     if (j + 3 < NT) SLOAD(SE, (j + 3) * KVBLK); SBAR();
;     pv_d0(o, vb0 + bp * SHM_V, pa0, pa1, pa2, pa3); partialSM(pA0, pA1, m_reg, alA, false);
.Lat_rescback0:
	s_waitcnt vmcnt(3)
	s_barrier
	s_mov_b32 s21, 0
	s_lshl_b32 s59, s1, 14
	v_add_u32_e32 v172, s59, v177
	s_lshl_b32 s20, s2, 14
	s_add_i32 s20, s20, s79
	s_add_i32 m0, s20, s79
	s_nop 0
	global_load_lds_dwordx4 v233, s[24:25]
	s_add_i32 m0, m0, 0x400
	s_nop 0
	global_load_lds_dwordx4 v234, s[24:25]
	s_add_i32 s20, s52, 4
	s_and_b32 s20, s20, 3
	s_lshl_b32 s20, s20, 13
	s_add_i32 s20, s20, s79
	s_add_i32 m0, s20, 0xc000
	s_nop 0
	global_load_lds_dwordx4 v232, s[24:25]
	s_add_u32 s24, s24, 0x10000
	s_addc_u32 s25, s25, 0
	v_add_f32_e32 v159, v96, v97
	v_cvt_pk_bf16_f32 v96, v96, v97
	v_add_f32_e32 v160, v98, v99
	v_cvt_pk_bf16_f32 v97, v98, v99
	v_add_f32_e32 v159, v100, v159
	s_waitcnt lgkmcnt(7)
	v_mfma_f32_32x32x16_bf16 v[64:79], v[182:185], v[124:127], v[128:143]
	ds_read_b64_tr_b16 v[182:183], v172 offset:0x0
	ds_read_b64_tr_b16 v[184:185], v172 offset:0x800
	v_add_f32_e32 v160, v101, v160
	v_cvt_pk_bf16_f32 v98, v100, v101
	v_add_f32_e32 v159, v102, v159
	v_add_f32_e32 v160, v103, v160
	v_cvt_pk_bf16_f32 v99, v102, v103
	v_add_f32_e32 v159, v104, v159
	s_waitcnt lgkmcnt(8)
	v_mfma_f32_32x32x16_bf16 v[80:95], v[186:189], v[124:127], v[128:143]
	ds_read_b64_tr_b16 v[186:187], v172 offset:0x1000
	ds_read_b64_tr_b16 v[188:189], v172 offset:0x1800
	v_add_f32_e32 v160, v105, v160
	v_cvt_pk_bf16_f32 v100, v104, v105
	v_add_f32_e32 v159, v106, v159
	v_add_f32_e32 v160, v107, v160
	v_cvt_pk_bf16_f32 v101, v106, v107
	s_waitcnt lgkmcnt(9)
	v_mfma_f32_32x32x16_bf16 v[64:79], v[190:193], v[120:123], v[64:79]
	ds_read_b64_tr_b16 v[190:191], v172 offset:0x2000
	ds_read_b64_tr_b16 v[192:193], v172 offset:0x2800
	v_add_f32_e32 v159, v108, v159
	v_add_f32_e32 v160, v109, v160
	v_cvt_pk_bf16_f32 v102, v108, v109
	v_add_f32_e32 v159, v110, v159
	v_add_f32_e32 v160, v111, v160
	v_cvt_pk_bf16_f32 v103, v110, v111
	s_waitcnt lgkmcnt(10)
	v_mfma_f32_32x32x16_bf16 v[80:95], v[194:197], v[120:123], v[80:95]
	ds_read_b64_tr_b16 v[194:195], v172 offset:0x3000
	ds_read_b64_tr_b16 v[196:197], v172 offset:0x3800
	v_add_f32_e32 v159, v236, v159
	v_add_f32_e32 v160, v237, v160
	v_cvt_pk_bf16_f32 v104, v236, v237
	v_add_f32_e32 v159, v238, v159
	v_add_f32_e32 v160, v239, v160
	v_cvt_pk_bf16_f32 v105, v238, v239
	s_waitcnt lgkmcnt(11)
	v_mfma_f32_32x32x16_bf16 v[64:79], v[198:201], v[116:119], v[64:79]
	ds_read_b64_tr_b16 v[198:199], v172 offset:0x200
	ds_read_b64_tr_b16 v[200:201], v172 offset:0xa00
	v_add_f32_e32 v159, v240, v159
	v_add_f32_e32 v160, v241, v160
	v_cvt_pk_bf16_f32 v106, v240, v241
	v_add_f32_e32 v159, v242, v159
	v_add_f32_e32 v160, v243, v160
	v_cvt_pk_bf16_f32 v107, v242, v243
	s_waitcnt lgkmcnt(12)
	v_mfma_f32_32x32x16_bf16 v[80:95], v[202:205], v[116:119], v[80:95]
	ds_read_b64_tr_b16 v[202:203], v172 offset:0x1200
	ds_read_b64_tr_b16 v[204:205], v172 offset:0x1a00
	v_add_f32_e32 v159, v244, v159
	v_add_f32_e32 v160, v245, v160
	v_cvt_pk_bf16_f32 v108, v244, v245
	v_add_f32_e32 v159, v246, v159
	v_add_f32_e32 v160, v247, v160
	v_cvt_pk_bf16_f32 v109, v246, v247
	v_add_f32_e32 v159, v248, v159
	s_waitcnt lgkmcnt(13)
	v_mfma_f32_32x32x16_bf16 v[64:79], v[206:209], v[112:115], v[64:79]
	ds_read_b64_tr_b16 v[206:207], v172 offset:0x2200
	ds_read_b64_tr_b16 v[208:209], v172 offset:0x2a00
	v_add_f32_e32 v160, v249, v160
	v_cvt_pk_bf16_f32 v110, v248, v249
	v_add_f32_e32 v159, v250, v159
	v_add_f32_e32 v160, v251, v160
	v_cvt_pk_bf16_f32 v111, v250, v251
	v_add_f32_e32 v159, v159, v160
	v_fma_f32 v167, v167, v158, v159
	s_waitcnt lgkmcnt(14)
	v_mfma_f32_32x32x16_bf16 v[80:95], v[210:213], v[112:115], v[80:95]
	s_waitcnt lgkmcnt(12)
	v_mfma_f32_32x32x16_bf16 v[0:15], v[96:99], v[182:185], v[0:15]
	ds_read_b64_tr_b16 v[210:211], v172 offset:0x3200
	ds_read_b64_tr_b16 v[212:213], v172 offset:0x3a00
	v_max3_f32 v161, v64, v65, v66
	v_max3_f32 v161, v161, v67, v68
	v_max3_f32 v161, v161, v69, v70
	v_max3_f32 v161, v161, v71, v72
	s_waitcnt lgkmcnt(12)
	v_mfma_f32_32x32x16_bf16 v[0:15], v[100:103], v[186:189], v[0:15]
	ds_read_b64_tr_b16 v[182:183], v172 offset:0x400
	ds_read_b64_tr_b16 v[184:185], v172 offset:0xc00
	v_max3_f32 v161, v161, v73, v74
	v_max3_f32 v161, v161, v75, v76
	v_max3_f32 v161, v161, v77, v78
	v_max_f32_e32 v161, v161, v79
	s_waitcnt lgkmcnt(12)
	v_mfma_f32_32x32x16_bf16 v[0:15], v[104:107], v[190:193], v[0:15]
	ds_read_b64_tr_b16 v[186:187], v172 offset:0x1400
	ds_read_b64_tr_b16 v[188:189], v172 offset:0x1c00
	v_max3_f32 v216, v80, v81, v82
	v_max3_f32 v216, v216, v83, v84
	v_max3_f32 v216, v216, v85, v86
	v_max3_f32 v216, v216, v87, v88
	s_waitcnt lgkmcnt(12)
	v_mfma_f32_32x32x16_bf16 v[0:15], v[108:111], v[194:197], v[0:15]
	ds_read_b64_tr_b16 v[190:191], v172 offset:0x2400
	ds_read_b64_tr_b16 v[192:193], v172 offset:0x2c00
	v_max3_f32 v216, v216, v89, v90
	v_max3_f32 v216, v216, v91, v92
	v_max3_f32 v216, v216, v93, v94
	v_max_f32_e32 v216, v216, v95
	v_max_f32_e32 v161, v161, v216
	v_cmp_ge_f32_e32 vcc, s66, v161
	s_cmp_eq_u64 vcc, exec
	s_cbranch_scc0 .Lat_rare1
	v_mov_b32_e32 v235, 1.0
